# XCD-phase stagger: odd XCDs sleep 5x127 once before the layer loop (v36 otherwise)
# speedup vs baseline: 1.0015x; 1.0006x over previous
; #define ws   (fresh_ptr(a.ws))
;     __host__ __device__ __forceinline__ bool next(int i, Unit& u) const {
;         const long L = (long)i * G + c; if (L >= nwg) return false;
;         int wgid = (int)L; { const int q = nwg / NXCD, r = nwg % NXCD, xcd = wgid % NXCD, off = wgid / NXCD; wgid = (xcd < r ? xcd * (q + 1) : r * (q + 1) + (xcd - r) * q) + off; }
;         const int nig = WGM * nN, gid = wgid / nig, fm = gid * WGM, gsz = (nM - fm) < WGM ? (nM - fm) : WGM;
;         u.pm = fm + ((wgid % nig) % gsz); u.pn = (wgid % nig) / gsz; return true;
; __global__ void __launch_bounds__(512, 2) fwd_megakernel(Args a) {
;     ...
;     for (int l = 0; l < DEPTH; ++l) {
;         unsigned char* wl = ws + WS_W + (size_t)l * W_LAYER;
;         { pg8::Gemm g{HB, (const bf16*)(wl + W_IN), M, DIN, D}; pg8::StaticOrder S; S.init(M, DIN, G, bx);
;           pg8::EpiBf16S E{PROJ, DIN, (size_t)256 * DIN, (size_t)256, slots, 1.0f, 2, VSTAT, 4, GAP_P};
;           for (int rep = 0; rep < REP_INP; ++rep) pg8::gemm_phase<pg8::EpiBf16S, pg8::StaticOrder, GEMM_ALIGN, GEMM_SP2>(lds, g, S, E, wave_s); }
.LBB0_260:
	s_cmpk_lt_i32 s92, 0x600
	s_cselect_b64 s[0:1], -1, 0
	v_writelane_b32 v253, s0, 50
	s_ashr_i32 s16, s92, 31
	s_lshl_b32 s4, s92, 6
	v_writelane_b32 v253, s1, 51
	s_lshr_b32 s0, s16, 29
	s_add_i32 s1, s92, s0
	s_and_b32 s2, s4, 0x1c0
	s_ashr_i32 s0, s1, 3
	s_and_b32 s1, s1, -8
	v_writelane_b32 v253, s2, 52
	s_sub_i32 s1, s92, s1
	v_readlane_b32 s6, v253, 0
	v_readlane_b32 s7, v253, 1
	s_add_u32 s4, s6, 0x200
	s_addc_u32 s5, s7, 0
	s_add_u32 s78, s6, 0x1000
	s_addc_u32 s79, s7, 0
	s_add_u32 s84, s6, 0x1100
	s_addc_u32 s85, s7, 0
	s_add_u32 s62, s6, 0x1200
	v_writelane_b32 v253, s4, 53
	s_addc_u32 s63, s7, 0
	s_mov_b32 s87, 0
	v_writelane_b32 v253, s5, 54
	s_add_u32 s4, s6, 0x1300
	s_addc_u32 s5, s7, 0
	v_writelane_b32 v253, s4, 55
	s_cmp_eq_u32 s33, 15
	v_mov_b32_e32 v193, 0
	v_writelane_b32 v253, s5, 56
	s_cselect_b64 s[4:5], -1, 0
	v_writelane_b32 v253, s4, 57
	s_cmp_eq_u32 s33, 14
	v_mov_b32_e32 v244, 0x358637bd
	v_writelane_b32 v253, s5, 58
	s_cselect_b64 s[4:5], -1, 0
	v_writelane_b32 v253, s4, 59
	s_cmp_eq_u32 s33, 13
	v_mov_b32_e32 v245, 1
	v_writelane_b32 v253, s5, 60
	s_cselect_b64 s[4:5], -1, 0
	v_writelane_b32 v253, s4, 61
	s_cmp_eq_u32 s33, 12
	v_mbcnt_hi_u32_b32 v252, -1, v158
	v_writelane_b32 v253, s5, 62
	s_cselect_b64 s[4:5], -1, 0
	v_writelane_b32 v253, s4, 63
	s_cmp_eq_u32 s33, 11
	v_readlane_b32 s14, v253, 43
	v_writelane_b32 v254, s5, 0
	s_cselect_b64 s[4:5], -1, 0
	v_writelane_b32 v254, s4, 1
	s_cmp_eq_u32 s33, 10
	v_readlane_b32 s15, v253, 44
	v_writelane_b32 v254, s5, 2
	s_cselect_b64 s[4:5], -1, 0
	v_writelane_b32 v254, s4, 3
	s_cmp_eq_u32 s33, 9
	v_mov_b32_e32 v242, 0xc00
	v_writelane_b32 v254, s5, 4
	s_cselect_b64 s[4:5], -1, 0
	v_writelane_b32 v254, s4, 5
	s_cmp_eq_u32 s33, 8
	v_mov_b64_e32 v[246:247], 0x400
	v_writelane_b32 v254, s5, 6
	s_cselect_b64 s[4:5], -1, 0
	v_writelane_b32 v254, s4, 7
	s_cmp_eq_u32 s33, 7
	s_movk_i32 s29, 0x1600
	v_writelane_b32 v254, s5, 8
	s_cselect_b64 s[4:5], -1, 0
	v_writelane_b32 v254, s4, 9
	s_cmp_eq_u32 s33, 6
	s_mov_b32 s35, 0x10000
	v_writelane_b32 v254, s5, 10
	s_cselect_b64 s[4:5], -1, 0
	v_writelane_b32 v254, s4, 11
	s_cmp_eq_u32 s33, 5
	s_mov_b32 s90, 0x14000
	v_writelane_b32 v254, s5, 12
	s_cselect_b64 s[4:5], -1, 0
	v_writelane_b32 v254, s4, 13
	s_cmp_eq_u32 s33, 4
	s_mov_b32 s65, 0x18000
	v_writelane_b32 v254, s5, 14
	s_cselect_b64 s[4:5], -1, 0
	v_writelane_b32 v254, s4, 15
	s_cmp_eq_u32 s33, 3
	s_mov_b32 s52, 0x1c000
	v_writelane_b32 v254, s5, 16
	s_cselect_b64 s[4:5], -1, 0
	v_writelane_b32 v254, s4, 17
	s_cmp_eq_u32 s33, 2
	s_mov_b32 s83, 0xffff4000
	v_writelane_b32 v254, s5, 18
	s_cselect_b64 s[4:5], -1, 0
	v_writelane_b32 v254, s4, 19
	s_cmp_eq_u32 s33, 1
	s_mov_b32 s37, 0xffff0000
	v_writelane_b32 v254, s5, 20
	s_cselect_b64 s[4:5], -1, 0
	v_writelane_b32 v254, s4, 21
	s_cmp_eq_u32 s33, 0
	s_movk_i32 s68, 0x7fff
	v_writelane_b32 v254, s5, 22
	s_cselect_b64 s[4:5], -1, 0
	v_writelane_b32 v254, s4, 23
	s_movk_i32 s70, 0x5800
	s_mov_b64 s[88:89], 0x80
	v_writelane_b32 v254, s5, 24
	s_lshl_b32 s4, s33, 8
	s_add_u32 s4, s6, s4
	s_addc_u32 s5, s7, 0
	s_add_u32 s10, s4, 0x1400
	s_addc_u32 s11, s5, 0
	v_writelane_b32 v254, s10, 25
	s_add_u32 s4, s4, 0x2400
	s_addc_u32 s5, s5, 0
	v_writelane_b32 v254, s11, 26
	v_writelane_b32 v254, s4, 27
	s_mov_b32 s28, 0x3e6d3388
	s_mov_b32 s30, 0x3f07dc22
	v_writelane_b32 v254, s5, 28
	s_add_u32 s4, s6, 0x3400
	s_addc_u32 s5, s7, 0
	v_writelane_b32 v254, s4, 29
	s_mov_b32 s36, 0x3f35f0e3
	s_mov_b32 s80, 0xbe11a98e
	v_writelane_b32 v254, s5, 30
	s_add_u32 s4, s6, 0x3500
	s_addc_u32 s5, s7, 0
	v_writelane_b32 v254, s4, 31
	s_mov_b32 s64, 0x3e027906
	s_nop 0
	v_writelane_b32 v254, s5, 32
	s_and_b64 s[4:5], s[14:15], exec
	s_cselect_b32 s2, 2, 0x80
	s_ashr_i32 s4, s92, 2
	v_writelane_b32 v254, s2, 33
	s_and_b32 s2, s4, -8
	s_lshl_b32 s4, s92, 2
	s_and_b32 s5, s4, 28
	s_bfe_u32 s6, s92, 0x20005
	v_writelane_b32 v254, s2, 34
	s_or_b32 s2, s6, s5
	s_lshl_b32 s5, s92, 10
	v_writelane_b32 v254, s2, 35
	s_and_b32 s5, s5, 0x1c00
	s_andn2_b32 s4, s4, 31
	v_readlane_b32 s2, v253, 19
	s_add_i32 s4, s5, s4
	s_lshl_b32 s5, s2, 2
	s_add_i32 s5, s4, s5
	s_lshl_b32 s4, s92, 8
	s_and_b32 s4, s4, 0x700
	s_and_b32 s6, s92, -8
	s_add_i32 s10, s4, s6
	s_cmpk_lt_i32 s92, 0x400
	s_cselect_b64 s[6:7], -1, 0
	s_lshl_b32 s4, s1, 7
	v_writelane_b32 v254, s6, 36
	s_cmpk_lt_i32 s92, 0x1600
	s_nop 0
	v_writelane_b32 v254, s7, 37
	s_cselect_b64 s[6:7], -1, 0
	v_writelane_b32 v254, s6, 38
	s_cmp_lt_i32 s1, 0
	s_nop 0
	v_writelane_b32 v254, s7, 39
	s_mul_i32 s6, s1, 0x81
	s_cselect_b32 s11, s6, s4
	s_movk_i32 s4, 0xc1
	s_cselect_b32 s4, s4, 0xc0
	s_mul_i32 s4, s1, s4
	s_movk_i32 s6, 0x2c1
	s_cselect_b32 s12, s6, 0x2c0
	s_add_i32 s4, s4, s0
	s_mul_hi_i32 s6, s4, 0x2aaaaaab
	s_lshr_b32 s7, s6, 31
	s_ashr_i32 s6, s6, 2
	s_add_i32 s6, s6, s7
	s_mul_i32 s7, s6, 24
	s_sub_i32 s4, s4, s7
	s_bfe_i32 s7, s4, 0x80000
	s_bfe_u32 s7, s7, 0x2000d
	s_add_i32 s7, s4, s7
	s_and_b32 s13, s7, 0xfc
	s_sub_i32 s4, s4, s13
	s_bfe_i32 s7, s7, 0x80000
	s_lshl_b32 s6, s6, 2
	s_sext_i32_i16 s7, s7
	s_sext_i32_i8 s4, s4
	s_add_i32 s18, s6, s4
	s_ashr_i32 s4, s7, 2
	v_writelane_b32 v254, s4, 40
	s_lshr_b32 s4, s7, 2
	s_and_b64 s[6:7], s[14:15], exec
	v_readlane_b32 s6, v253, 40
	v_readlane_b32 s7, v253, 41
	s_cselect_b32 s77, 1, s6
	v_readlane_b32 s6, v253, 38
	v_readlane_b32 s7, v253, 39
	s_cselect_b32 s13, s5, s6
	s_add_i32 s5, s5, 4
	s_and_b64 s[6:7], s[14:15], exec
; __device__ __forceinline__ unsigned xb_ld(unsigned* p)              { return __hip_atomic_load(p, __ATOMIC_RELAXED, __HIP_MEMORY_SCOPE_AGENT); }
; __device__ __forceinline__ unsigned xb_add(unsigned* p, unsigned v) { return __hip_atomic_fetch_add(p, v, __ATOMIC_RELAXED, __HIP_MEMORY_SCOPE_AGENT); }
; #define XB_SPIN(cond, bar) do { unsigned _sp = 0; while (cond) { __builtin_amdgcn_s_sleep(1); \
;     if ((++_sp & 255u) == 0u) { if (xb_ld(&(bar)[XB_TMO])) break; if (_sp > XB_SPIN_CAP) { atomicAdd(&(bar)[XB_TMO], 1u); break; } } } } while (0)
;     __host__ __device__ __forceinline__ bool next(int i, Unit& u) const {
;         const long L = (long)i * G + c; if (L >= nwg) return false;
;         int wgid = (int)L; { const int q = nwg / NXCD, r = nwg % NXCD, xcd = wgid % NXCD, off = wgid / NXCD; wgid = (xcd < r ? xcd * (q + 1) : r * (q + 1) + (xcd - r) * q) + off; }
;         const int nig = WGM * nN, gid = wgid / nig, fm = gid * WGM, gsz = (nM - fm) < WGM ? (nM - fm) : WGM;
;         u.pm = fm + ((wgid % nig) % gsz); u.pn = (wgid % nig) / gsz; return true;
; __device__ __forceinline__ void xcd_barrier(const XcdBarrier& b) {
;     asm volatile("s_waitcnt vmcnt(0)" ::: "memory");
;     __syncthreads();
;     if (threadIdx.x == 0) {
;         unsigned* bar = b.bar;
;         __builtin_amdgcn_s_waitcnt(0);
;         unsigned nloc = b.st[0], nx = b.st[1];
;         if (nloc == 0u) { xcd_barrier_complete(bar, b.x, nloc, nx); b.st[0] = nloc; b.st[1] = nx; }
;         const unsigned old = xb_add(&bar[XB_XSUB(b.x)], 1u);
;         const unsigned gen = old / nloc;
;         if (old + 1u == (gen + 1u) * nloc) {
;             __builtin_amdgcn_fence(__ATOMIC_RELEASE, "agent");
;             asm volatile("s_waitcnt vmcnt(0)" ::: "memory");
;             const unsigned og = xb_add(&bar[XB_TOP], 1u);
;             const unsigned tg = og / nx;
;             if (og + 1u == (tg + 1u) * nx) xb_add(&bar[XB_TOPGEN], 1u);
;             else XB_SPIN(xb_ld(&bar[XB_TOPGEN]) == tg, bar);
;             __builtin_amdgcn_fence(__ATOMIC_ACQUIRE, "agent");
;             xb_add(&bar[XB_XGEN(b.x)], 1u);
	s_cselect_b32 s6, s10, s61
	s_cselect_b32 s10, s5, 0x2000
	s_add_i32 s2, s6, s2
	s_add_i32 s5, s2, 1
	s_and_b64 s[6:7], s[14:15], exec
	s_cselect_b32 s14, s5, 0x800
	s_cmp_lt_i32 s13, s10
	v_writelane_b32 v254, s10, 41
	s_cselect_b64 s[6:7], -1, 0
	v_writelane_b32 v254, s6, 42
	s_lshl_b32 s5, s13, 5
	s_mul_i32 s1, s1, s12
	v_writelane_b32 v254, s7, 43
	s_ashr_i32 s6, s13, 4
	s_ashr_i32 s7, s6, 31
	s_lshl_b64 s[20:21], s[6:7], 7
	s_and_b32 s6, s5, 0x60
	s_or_b32 s20, s20, s6
	v_writelane_b32 v254, s20, 44
	s_and_b32 s86, s20, 0x1fe0
	s_cmp_lg_u64 s[86:87], 0
	s_mov_b32 s7, s16
	v_writelane_b32 v254, s21, 45
	s_cselect_b64 s[16:17], -1, 0
	v_writelane_b32 v254, s16, 46
	s_and_b32 s5, s5, 0x180
	s_cmp_lt_i32 s2, s14
	v_writelane_b32 v254, s17, 47
	v_writelane_b32 v254, s5, 48
	v_writelane_b32 v254, s14, 49
	s_cselect_b64 s[14:15], -1, 0
	s_add_i32 s5, s11, s0
	s_ashr_i32 s6, s5, 31
	s_lshr_b32 s6, s6, 28
	s_add_i32 s6, s5, s6
	s_and_b32 s10, s6, 0xfff0
	s_sub_i32 s5, s5, s10
	s_bfe_i32 s10, s5, 0x80000
	s_bfe_u32 s10, s10, 0x2000d
	s_add_i32 s10, s5, s10
	s_add_i32 s1, s1, s0
	s_and_b32 s11, s10, 0xfc
	s_mul_hi_i32 s0, s1, 0x2e8ba2e9
	s_sub_i32 s5, s5, s11
	s_lshr_b32 s11, s0, 31
	s_ashr_i32 s0, s0, 4
	s_add_i32 s0, s0, s11
	s_mul_i32 s11, s0, 0x58
	s_sub_i32 s1, s1, s11
	s_bfe_i32 s11, s1, 0x80000
	s_bfe_u32 s11, s11, 0x2000d
	s_add_i32 s11, s1, s11
	s_and_b32 s12, s11, 0xfc
	s_ashr_i32 s6, s6, 4
	v_writelane_b32 v254, s14, 50
	s_sub_i32 s1, s1, s12
	s_lshl_b32 s6, s6, 2
	s_sext_i32_i8 s5, s5
	v_writelane_b32 v254, s15, 51
	s_add_i32 s14, s6, s5
	s_lshl_b32 s0, s0, 2
	s_bfe_i32 s5, s11, 0x80000
	s_sext_i32_i8 s1, s1
	s_add_i32 s16, s0, s1
	s_bfe_i64 s[0:1], s[4:5], 0x100000
	s_bfe_i32 s10, s10, 0x80000
	s_lshl_b64 s[0:1], s[0:1], 19
	s_sext_i32_i16 s10, s10
	v_writelane_b32 v254, s0, 52
	s_ashr_i32 s4, s10, 2
	s_sext_i32_i16 s6, s5
	v_writelane_b32 v254, s1, 53
	v_writelane_b32 v254, s4, 54
	s_lshr_b32 s4, s10, 2
	s_bfe_i64 s[4:5], s[4:5], 0x100000
	s_lshl_b64 s[4:5], s[4:5], 19
	v_writelane_b32 v254, s4, 55
	s_ashr_i32 s19, s18, 31
	s_lshl_b64 s[10:11], s[18:19], 19
	v_writelane_b32 v254, s5, 56
	s_ashr_i32 s4, s6, 2
	v_writelane_b32 v254, s4, 57
	s_lshr_b32 s4, s6, 2
	s_bfe_i64 s[4:5], s[4:5], 0x100000
	s_lshl_b64 s[4:5], s[4:5], 19
	v_writelane_b32 v254, s4, 58
	s_ashr_i32 s15, s14, 31
	s_ashr_i32 s0, s14, 5
	v_writelane_b32 v254, s5, 59
	v_writelane_b32 v254, s13, 60
	v_writelane_b32 v254, s2, 61
	s_lshl_b32 s2, s2, 7
	v_writelane_b32 v254, s2, 62
	s_lshl_b32 s2, s77, 7
	v_writelane_b32 v254, s2, 63
	s_mov_b32 s2, s18
	v_writelane_b32 v255, s2, 0
	s_ashr_i32 s1, s0, 31
	s_ashr_i32 s17, s16, 31
	v_writelane_b32 v255, s3, 1
	v_writelane_b32 v255, s10, 2
	s_mov_b32 s2, s14
	s_ashr_i32 s4, s13, 10
	v_writelane_b32 v255, s11, 3
	v_writelane_b32 v255, s2, 4
	s_lshl_b64 s[10:11], s[14:15], 19
	s_nop 0
	v_writelane_b32 v255, s3, 5
	v_writelane_b32 v255, s10, 6
	s_mov_b32 s2, s16
	s_nop 0
	v_writelane_b32 v255, s11, 7
	s_lshl_b64 s[10:11], s[0:1], 21
	v_writelane_b32 v255, s10, 8
	s_nop 1
	v_writelane_b32 v255, s11, 9
	v_writelane_b32 v255, s2, 10
	s_lshl_b64 s[10:11], s[16:17], 19
	v_readlane_b32 s12, v253, 20
	v_writelane_b32 v255, s3, 11
	v_readlane_b32 s13, v253, 21
	v_readlane_b32 s24, v253, 32
	v_readlane_b32 s25, v253, 33
	v_writelane_b32 v255, s10, 12
	s_mov_b64 s[12:13], s[24:25]
	s_add_u32 s1, s12, 16
	v_writelane_b32 v255, s11, 13
	v_writelane_b32 v255, s1, 14
	s_addc_u32 s1, s13, 0
	v_writelane_b32 v255, s1, 15
	s_mul_i32 s1, s9, s8
	s_mul_i32 s81, s1, s60
	s_mul_hi_i32 s1, s0, 0x1c00000
	v_writelane_b32 v255, s1, 16
	s_mul_i32 s0, s0, 0x1c00000
	v_writelane_b32 v255, s0, 17
	s_mul_hi_i32 s0, s4, 0x1400000
	v_writelane_b32 v255, s0, 18
	s_mul_i32 s0, s4, 0x1400000
	v_writelane_b32 v255, s0, 19
	s_mov_b32 s0, 0x21408
	s_addk_i32 s0, 0x100
	v_writelane_b32 v255, s0, 20
	s_mov_b32 s0, 0x21400
	s_addk_i32 s0, 0x100
	v_writelane_b32 v255, s0, 21
	s_mov_b32 s0, 0x21404
	s_addk_i32 s0, 0x100
	v_writelane_b32 v255, s0, 22
	s_movk_i32 s0, 0xff0
	s_addk_i32 s0, 0x100
	v_writelane_b32 v255, s0, 23
	s_mov_b32 s0, 0x22000
	s_addk_i32 s0, 0x100
	v_writelane_b32 v255, s0, 24
	s_mov_b32 s0, 0x23000
	s_add_i32 s6, s0, 0x100
	s_mov_b64 s[0:1], -1
	v_writelane_b32 v255, s0, 25
	v_readlane_b32 s14, v253, 22
	v_readlane_b32 s15, v253, 23
	v_writelane_b32 v255, s1, 26
	v_writelane_b32 v255, s7, 27
	v_writelane_b32 v255, s78, 28
	s_mov_b32 s0, s92
	v_readlane_b32 s16, v253, 24
	v_writelane_b32 v255, s79, 29
	v_writelane_b32 v255, s84, 30
	v_readlane_b32 s17, v253, 25
	v_readlane_b32 s18, v253, 26
	v_writelane_b32 v255, s85, 31
	v_writelane_b32 v255, s62, 32
	v_readlane_b32 s19, v253, 27
	v_readlane_b32 s20, v253, 28
	v_writelane_b32 v255, s63, 33
	v_writelane_b32 v255, s77, 34
	v_readlane_b32 s21, v253, 29
	v_readlane_b32 s22, v253, 30
	v_readlane_b32 s23, v253, 31
	v_readlane_b32 s26, v253, 34
	v_readlane_b32 s27, v253, 35
	v_writelane_b32 v253, s0, 20
	v_writelane_b32 v255, s81, 35
	s_mov_b32 s4, s87
	v_writelane_b32 v253, s1, 21
	v_writelane_b32 v255, s6, 36
	s_bitcmp1_b32 s92, 0
	s_cbranch_scc0 .Lxstag_skip
	s_sleep 127
	s_sleep 127
	s_sleep 127
	s_sleep 127
	s_sleep 127
.Lxstag_skip:
	s_branch .LBB0_264
.LBB0_261:
	s_or_b64 exec, exec, s[4:5]
	v_readlane_b32 s4, v254, 27
	v_readlane_b32 s5, v254, 28
	s_waitcnt vmcnt(0) lgkmcnt(0)
	buffer_inv sc1
	v_mov_b64_e32 v[0:1], s[4:5]
	flat_atomic_add v[0:1], v245
	s_waitcnt vmcnt(0)
